# c6 plus static s_setprio 1 for waves 4-7 across all attention units (C, D, A) of the mix phase
# baseline (speedup 1.0000x reference)
; template <int MODE>
; DI void attn_unit(unsigned char* lds, const AttnParams& ap, int b, int h, int qb, int tid) {
;     ...
;   const int wave = tid >> 6, lane = tid & 63, r32 = lane & 31, hi = lane >> 5, bh = b * 4 + h;
;   constexpr int qcol0 = (MODE == 0) ? C_AQ : (MODE == 1) ? C_CQ : C_DQ, kcol0 = (MODE == 0) ? C_AK : (MODE == 1) ? C_CK : C_DK, ycol0 = (MODE == 0) ? 0 : (MODE == 1) ? 512 : 768;
;   const bf16_t* Vt = ap.Vt + (size_t)((MODE == 0) ? 0 : (MODE == 1) ? 2 : 3) * T_ * 256;
;   const size_t tokb = (size_t)b * SEQ;
;   const int qpos = qb * 256 + wave * 32 + r32, cw = qb * 4 + (wave >> 1);
;   bf16x8 qf[4];
;   { const bf16_t* qp = ap.P + (tokb + qpos) * PLD + qcol0 + h * 64 + 8 * hi;
; #pragma unroll
;     for (int ks = 0; ks < 4; ++ks) qf[ks] = *(const bf16x8*)(qp + 16 * ks); }
;   bf16_t* Ks0 = (bf16_t*)lds; bf16_t* Vs0 = Ks0 + NCH * 64 * 72; volatile int* flags = (volatile int*)(lds + 2 * NCH * 64 * 72 * 2);
;   const int jhi = 4 * qb + 3, jlo = (MODE == 0) ? ((4 * qb - 8 > 0) ? 4 * qb - 8 : 0) : 0, ntiles = jhi - jlo + 1;
;   const int lrow = tid >> 3, lch = tid & 7;
;   const bf16_t* kg = ap.P + (tokb + lrow) * PLD + kcol0 + h * 64 + 8 * lch;
;   const bf16_t* vg = Vt + (size_t)bh * 256 * 4096 + lrow * 64 + 8 * lch;
;   const int j0 = (MODE == 2) ? jhi : jlo;
;   u32x4 kreg[NCH], vreg[NCH];
; #pragma unroll
;   for (int c = 0; c < NCH; ++c) { const int jc = (MODE == 2) ? j0 - c : j0 + c; kreg[c] = *(const u32x4*)(kg + (size_t)jc * 64 * PLD); vreg[c] = *(const u32x4*)(vg + (size_t)jc * 4096); }
;   f32x16 O0[2], O1[2]; float l0 = 0.f, l1 = 0.f, cum = 0.f;
; DI void mix_phase(unsigned char* lds, const MixParams& mp, int tid) {
;     ...
;   for (;;) {
;     __syncthreads();
;     if (tid == 0) misc[0] = (int)atomicAdd(mp.ctr, 1u);
;     __syncthreads();
;     const int it = misc[0];
;     constexpr int NB2 = 17;
;     if (it >= NB2 + 3 * 512) break;
;     if (it < NB2) { b2_item(mp.DC, mp.SC, it, lds, tid); continue; }
;     const int r = (it - NB2) & 511, kind = (it - NB2) >> 9, qb = 63 - (r >> 3), bh = r & 7, b = bh >> 2, h = bh & 3;
;     if (kind == 0) { ap.negM = -MC; ap.lam = lam; ap.oscale = 1.0f - mp.lam_init; ap.cgain = mp.cog; attn_unit<1>(lds, ap, b, h, qb, tid); }
;     else if (kind == 1) { attn_unit<2>(lds, ap, b, h, qb, tid); }
;     else { ap.negM = -(MA + red[4 + h]); ap.biasL = biasT + h * 260; attn_unit<0>(lds, ap, b, h, qb, tid); }
.LBB0_805:
	s_or_b64 exec, exec, s[0:1]
	s_add_i32 s0, 0, 0x20000
	s_cmp_lg_u32 s0, -1
	s_cselect_b32 s0, s0, 0
	s_cselect_b32 s1, s83, 0
	v_mov_b32_e32 v0, s0
	v_mov_b32_e32 v1, s1
	s_waitcnt lgkmcnt(0)
	s_barrier
	flat_load_dword v6, v[0:1] sc0 sc1
	s_waitcnt vmcnt(0)
	s_movk_i32 s0, 0x611
	s_waitcnt lgkmcnt(0)
	v_cmp_gt_i32_e32 vcc, s0, v6
	s_mov_b64 s[0:1], -1
	s_and_saveexec_b64 s[90:91], vcc
	s_cbranch_execz .LBB0_800
	v_cmp_lt_i32_e32 vcc, 16, v6
	s_and_saveexec_b64 s[0:1], vcc
	s_xor_b64 s[22:23], exec, s[0:1]
	s_cbranch_execz .LBB0_854
	v_readfirstlane_b32 s0, v156
	s_nop 3
	s_cmp_ge_u32 s0, 256
	s_cbranch_scc0 .Lmix_noprio
	s_setprio 1
.Lmix_noprio:
	v_subrev_u32_e32 v7, 17, v6
	v_not_b32_e32 v0, v7
	s_movk_i32 s0, 0x1ff
	v_bfe_u32 v0, v0, 3, 6
	v_bfe_u32 v4, v7, 2, 1
	v_and_b32_e32 v5, 3, v7
	v_cmp_lt_u32_e32 vcc, s0, v7
	s_and_saveexec_b64 s[0:1], vcc
	s_xor_b64 s[0:1], exec, s[0:1]
	v_writelane_b32 v255, s0, 51
	s_nop 1
	v_writelane_b32 v255, s1, 52
	s_cbranch_execz .LBB0_845
	v_and_b32_e32 v1, 0xfffffe00, v7
	s_movk_i32 s0, 0x200
	v_cmp_ne_u32_e32 vcc, s0, v1
	v_lshlrev_b32_e32 v155, 8, v0
	s_and_saveexec_b64 s[0:1], vcc
	s_xor_b64 s[0:1], exec, s[0:1]
	s_cbranch_execz .LBB0_826
	v_readlane_b32 s2, v254, 39
	v_mov_b32_e32 v7, v156
	v_lshlrev_b32_e32 v3, 8, v0
	v_lshl_add_u32 v1, v5, 2, s2
	ds_read_b32 v8, v1 offset:16
	v_lshlrev_b32_e32 v32, 14, v4
	v_ashrrev_i32_e32 v6, 1, v7
	v_and_b32_e32 v6, 0xffffffe0, v6
	v_and_b32_e32 v1, 31, v7
	v_add_u32_e32 v9, v6, v3
	v_or_b32_e32 v10, v9, v1
	v_ashrrev_i32_e32 v11, 31, v10
	v_lshlrev_b32_e32 v9, 2, v0
	v_lshl_add_u64 v[108:109], v[10:11], 0, v[32:33]
	v_add_u32_e32 v11, -8, v9
	v_cmp_lt_u32_e32 vcc, 2, v0
	v_or_b32_e32 v0, 3, v9
	v_bfe_u32 v2, v7, 5, 1
	v_cndmask_b32_e32 v110, 0, v11, vcc
	v_lshlrev_b32_e32 v10, 6, v5
	v_sub_u32_e32 v116, v0, v110
	v_cmp_lt_i32_e32 vcc, -1, v116
	v_lshlrev_b32_e32 v46, 1, v10
	v_lshlrev_b32_e32 v34, 2, v2
	s_and_saveexec_b64 s[2:3], vcc
	s_xor_b64 s[2:3], exec, s[2:3]
	s_cbranch_execz .LBB0_823
	v_readlane_b32 s4, v255, 25
	v_readlane_b32 s5, v255, 26
	v_mov_b32_e32 v47, v33
	v_lshlrev_b32_e32 v14, 4, v2
	v_mov_b64_e32 v[10:11], s[4:5]
	v_mad_u64_u32 v[12:13], s[4:5], v108, s82, v[10:11]
	v_mad_i32_i24 v13, v109, s82, v13
	v_lshl_add_u64 v[12:13], v[12:13], 0, v[46:47]
	v_mov_b32_e32 v15, v33
	v_lshl_add_u64 v[12:13], v[12:13], 0, v[14:15]
	v_ashrrev_i32_e32 v0, 3, v7
	global_load_dwordx4 v[34:37], v[12:13], off
	global_load_dwordx4 v[38:41], v[12:13], off offset:32
	global_load_dwordx4 v[42:45], v[12:13], off offset:64
	global_load_dwordx4 v[96:99], v[12:13], off offset:96
	v_add_u32_e32 v12, v0, v32
	v_mad_i64_i32 v[10:11], s[4:5], v12, s82, v[10:11]
	v_lshlrev_b32_e32 v12, 4, v7
	v_lshl_add_u64 v[10:11], v[10:11], 0, v[46:47]
	v_and_b32_e32 v32, 0x70, v12
	v_lshl_add_u64 v[112:113], v[10:11], 0, v[32:33]
	v_lshlrev_b32_e32 v10, 21, v5
	v_readlane_b32 s4, v255, 27
	v_lshl_or_b32 v10, v4, 23, v10
	v_mov_b32_e32 v11, v33
	v_readlane_b32 s5, v255, 28
	v_lshlrev_b32_e32 v12, 6, v0
	v_ashrrev_i32_e32 v13, 31, v12
	v_lshl_add_u64 v[10:11], s[4:5], 0, v[10:11]
	v_lshl_add_u64 v[10:11], v[12:13], 1, v[10:11]
	v_mov_b32_e32 v111, v33
	v_lshl_add_u64 v[114:115], v[10:11], 0, v[32:33]
	v_lshlrev_b64 v[10:11], 13, v[110:111]
	v_lshl_add_u64 v[10:11], v[114:115], 0, v[10:11]
	s_mov_b32 s4, 0x68800
	global_load_dwordx4 v[100:103], v[10:11], off
	v_mad_u64_u32 v[10:11], s[4:5], v110, s4, v[112:113]
	global_load_dwordx4 v[104:107], v[10:11], off offset:512
	v_mul_lo_u32 v0, v0, s68
	v_add3_u32 v119, 0, v32, v0
	v_lshlrev_b32_e32 v32, 2, v2
	v_mul_u32_u24_e32 v2, 0x90, v1
	v_add3_u32 v1, v3, v6, v1
	s_add_i32 s4, 0, 0x14000
	v_ashrrev_i32_e32 v117, 7, v7
	v_sub_u32_e32 v1, v1, v32
	v_lshlrev_b32_e32 v3, 6, v110
	v_mov_b32_e32 v4, s4
	s_movk_i32 s4, 0x410
	v_add_u32_e32 v118, v117, v9
	v_add_u32_e32 v0, 0, v14
	v_sub_u32_e32 v121, v9, v110
	v_sub_u32_e32 v1, v1, v3
	v_mov_b32_e32 v125, 0
	s_waitcnt lgkmcnt(0)
	v_add_f32_e32 v47, v152, v8
	v_mad_u32_u24 v111, v5, s4, v4
	v_add_u32_e32 v120, -8, v118
	v_add_u32_e32 v122, 4, v121
	v_subrev_u32_e32 v123, 27, v1
	s_mov_b32 s10, 0
	s_mov_b64 s[4:5], 0
	v_add_u32_e32 v124, v0, v2
	v_mov_b32_e32 v0, 0
	v_mov_b32_e32 v1, v125
	v_mov_b32_e32 v2, v125
	v_mov_b32_e32 v3, v125
	v_mov_b32_e32 v4, v125
	v_mov_b32_e32 v5, v125
	v_mov_b32_e32 v6, v125
	v_mov_b32_e32 v7, v125
	v_mov_b32_e32 v8, v125
	v_mov_b32_e32 v9, v125
	v_mov_b32_e32 v10, v125
	v_mov_b32_e32 v11, v125
	v_mov_b32_e32 v12, v125
	v_mov_b32_e32 v13, v125
	v_mov_b32_e32 v14, v125
	v_mov_b32_e32 v15, v125
	v_mov_b32_e32 v16, 0
	v_mov_b32_e32 v17, v125
	v_mov_b32_e32 v18, v125
	v_mov_b32_e32 v19, v125
	v_mov_b32_e32 v20, v125
	v_mov_b32_e32 v21, v125
	v_mov_b32_e32 v22, v125
	v_mov_b32_e32 v23, v125
	v_mov_b32_e32 v24, v125
	v_mov_b32_e32 v25, v125
	v_mov_b32_e32 v26, v125
	v_mov_b32_e32 v27, v125
	v_mov_b32_e32 v28, v125
	v_mov_b32_e32 v29, v125
	v_mov_b32_e32 v30, v125
	v_mov_b32_e32 v31, v125
	s_branch .LBB0_813

; DI void b2_item(float* DC, float* SC, int j, unsigned char* lds, int tid) {
;     ...
;   const int ge = j * 512 + tid, bh0 = (j * 512) / 1040, bh1 = (j * 512 + 511) / 1040;
;   { const int slot = tid >> 8, c = tid & 255, bh = slot ? bh1 : bh0;
;     if (bh < 8) { L[slot * 1024 + c] = SC[bh * 256 + c]; L[slot * 1024 + 256 + c] = SC[2048 + bh * 256 + c]; } }
;   __syncthreads();
; DI void mix_phase(unsigned char* lds, const MixParams& mp, int tid) {
;     ...
;     if (it < NB2) { b2_item(mp.DC, mp.SC, it, lds, tid); continue; }
.LBB0_854:
	s_setprio 0
	s_andn2_saveexec_b64 s[8:9], s[22:23]
	s_cbranch_execz .LBB0_799
	v_lshlrev_b32_e32 v6, 9, v6
	s_mov_b32 s0, 0x7e07e07f
	v_mul_hi_i32 v0, v6, s0
	v_lshrrev_b32_e32 v1, 31, v0
	v_ashrrev_i32_e32 v0, 9, v0
	v_add_u32_e32 v4, v0, v1
	v_or_b32_e32 v0, 0x1ff, v6
	v_mul_hi_i32 v0, v0, s0
	v_mov_b32_e32 v5, v156
	v_lshrrev_b32_e32 v1, 31, v0
	v_ashrrev_i32_e32 v0, 9, v0
	s_movk_i32 s0, 0x100
	v_add_u32_e32 v0, v0, v1
	v_cmp_gt_u32_e32 vcc, s0, v5
	s_mov_b32 s12, 0x7e07e07f
	s_nop 0
	v_cndmask_b32_e32 v1, v0, v4, vcc
	v_cmp_gt_i32_e32 vcc, 8, v1
	s_and_saveexec_b64 s[0:1], vcc
	s_cbranch_execz .LBB0_857
	v_and_b32_e32 v7, 0xff, v5
	v_lshl_or_b32 v2, v1, 8, v7
	v_readlane_b32 s2, v255, 33
	v_ashrrev_i32_e32 v3, 31, v2
	v_readlane_b32 s3, v255, 34
	v_lshlrev_b32_e32 v7, 2, v7
	s_nop 0
	v_lshl_add_u64 v[8:9], v[2:3], 2, s[2:3]
	v_lshlrev_b32_e32 v3, 4, v5
	v_and_b32_e32 v3, 0xfffff000, v3
	v_add_u32_e32 v2, 0x800, v2
	v_add3_u32 v7, 0, v3, v7
	v_ashrrev_i32_e32 v3, 31, v2
	v_lshl_add_u64 v[2:3], v[2:3], 2, s[2:3]
	global_load_dword v1, v[8:9], off
	s_nop 0
	global_load_dword v2, v[2:3], off
	s_waitcnt vmcnt(0)
	ds_write2st64_b32 v7, v1, v2 offset1:4
